# hand-scheduled SGU wave task in P4: u/bias loads hoisted to task start, K-steps double-buffered in registers
# speedup vs baseline: 1.0099x; 1.0093x over previous
; __device__ __forceinline__ void p4_sgu_task(const bf16_t* Wsgu, const bf16_t* VT, const bf16_t* U, const float* sgu_b, bf16_t* MIX, int strip, int h, int lane) {
;     const int fr = lane & 15, fq = lane >> 4;
;     const int tok0 = strip * 16, cmask = tok0 < TP ? 127 : 63, t0 = tok0 & cmask, cstart = tok0 - t0;
;     const int nks = (t0 + 16 + 31) >> 5;
;     f32x4 acc[8];
; #pragma unroll
;     for (int i = 0; i < 8; ++i) acc[i] = (f32x4){0.f, 0.f, 0.f, 0.f};
;     const bf16_t* wrow = Wsgu + ((size_t)h * 128 + t0 + fr) * 128 + 8 * fq;
;     for (int kk = 0; kk < nks; ++kk) {
;         const bf16x8 a = *(const bf16x8*)(wrow + 32 * kk);
;         const int sabs = cstart + 32 * kk;
;         const bf16_t* vb = VT + (((size_t)(sabs >> 6) * 8 + h) * 128 + fr) * 64 + (sabs & 63) + 8 * fq;
; #pragma unroll
;         for (int nf = 0; nf < 8; ++nf) { const bf16x8 b = *(const bf16x8*)(vb + (size_t)(16 * nf) * 64); acc[nf] = __builtin_amdgcn_mfma_f32_16x16x32_bf16(b, a, acc[nf], 0, 0, 0); }
;     }
.LBB0_674:
	s_cmpk_gt_i32 s3, 0x11ff
	s_mov_b64 s[8:9], -1
	s_cbranch_scc0 .LBB0_678
	s_add_i32 s11, s3, 0xffffee00
	s_load_dwordx2 s[8:9], s[12:13], 0x58
	s_lshl_b32 s10, s11, 1
	s_cmpk_lt_u32 s11, 0x2000
	s_cselect_b32 s11, 0x70, 48
	s_and_b32 s11, s11, s10
	s_and_b32 s22, s10, 0x7ffffff0
	s_add_i32 s27, s11, 47
	s_lshr_b32 s33, s27, 5
	s_lshl_b32 s27, s3, 7
	s_and_b32 s27, s27, 0x380
	s_sub_i32 s34, s22, s11
	s_lshl_b32 s42, s7, 8
	s_and_b32 s42, s42, 0x38000
	v_or_b32_e32 v216, s22, v63
	v_mov_b32_e32 v217, 0
	v_or_b32_e32 v246, s27, v148
	v_lshlrev_b32_e32 v246, 1, v246
	v_mov_b32_e32 v247, 0
	v_lshlrev_b64 v[242:243], 11, v[216:217]
	v_lshl_add_u64 v[242:243], s[20:21], 0, v[242:243]
	v_lshl_add_u64 v[242:243], v[242:243], 0, v[246:247]
	global_load_dwordx2 v[224:225], v[242:243], off
	global_load_dwordx2 v[226:227], v[242:243], off offset:32
	global_load_dwordx2 v[228:229], v[242:243], off offset:64
	global_load_dwordx2 v[230:231], v[242:243], off offset:96
	global_load_dwordx2 v[232:233], v[242:243], off offset:128
	global_load_dwordx2 v[234:235], v[242:243], off offset:160
	global_load_dwordx2 v[236:237], v[242:243], off offset:192
	global_load_dwordx2 v[238:239], v[242:243], off offset:224
	v_lshlrev_b64 v[244:245], 12, v[216:217]
	v_lshl_add_u64 v[244:245], s[16:17], 0, v[244:245]
	v_lshl_add_u64 v[244:245], v[244:245], 0, v[246:247]
	v_or_b32_e32 v36, s27, v63
	v_or_b32_e32 v240, s11, v36
	v_lshlrev_b32_e32 v240, 2, v240
	v_lshlrev_b32_e32 v60, 7, v36
	v_lshl_add_u64 v[32:33], s[14:15], 0, v[60:61]
	v_or_b32_e32 v0, s11, v63
	v_lshl_or_b32 v60, v0, 8, s42
	v_lshl_add_u64 v[34:35], v[80:81], 0, v[60:61]
	s_waitcnt lgkmcnt(0)
	global_load_dword v240, v240, s[8:9]
	s_ashr_i32 s42, s34, 6
	s_ashr_i32 s43, s42, 31
	s_and_b32 s22, s34, 48
	s_lshl_b64 s[42:43], s[42:43], 17
	s_lshl_b32 s22, s22, 1
	v_lshl_add_u64 v[210:211], v[32:33], 0, s[42:43]
	v_lshl_add_u64 v[210:211], v[210:211], 0, s[22:23]
	v_lshl_add_u64 v[210:211], v[210:211], 0, v[82:83]
	s_mov_b32 s42, 0x2000
	s_mov_b32 s43, 0
	global_load_dwordx4 v[158:161], v[34:35], off
	v_lshl_add_u64 v[212:213], v[210:211], 0, s[42:43]
	s_mov_b32 s42, 0x3000
	global_load_dwordx4 v[162:165], v[210:211], off
	global_load_dwordx4 v[166:169], v[210:211], off offset:2048
	v_lshl_add_u64 v[214:215], v[210:211], 0, s[42:43]
	global_load_dwordx4 v[170:173], v[212:213], off offset:-4096
	global_load_dwordx4 v[174:177], v[212:213], off offset:-2048
	global_load_dwordx4 v[178:181], v[212:213], off
	global_load_dwordx4 v[182:185], v[212:213], off offset:2048
	global_load_dwordx4 v[186:189], v[214:215], off
	global_load_dwordx4 v[190:193], v[214:215], off offset:2048
	s_add_i32 s34, s34, 32
	v_lshl_add_u64 v[34:35], v[34:35], 0, 64
	v_mov_b32_e32 v0, 0
	v_mov_b32_e32 v1, 0
	v_mov_b32_e32 v2, 0
	v_mov_b32_e32 v3, 0
	v_mov_b32_e32 v4, 0
	v_mov_b32_e32 v5, 0
	v_mov_b32_e32 v6, 0
	v_mov_b32_e32 v7, 0
	v_mov_b32_e32 v8, 0
	v_mov_b32_e32 v9, 0
	v_mov_b32_e32 v10, 0
	v_mov_b32_e32 v11, 0
	v_mov_b32_e32 v12, 0
	v_mov_b32_e32 v13, 0
	v_mov_b32_e32 v14, 0
	v_mov_b32_e32 v15, 0
	v_mov_b32_e32 v16, 0
	v_mov_b32_e32 v17, 0
	v_mov_b32_e32 v18, 0
	v_mov_b32_e32 v19, 0
	v_mov_b32_e32 v20, 0
	v_mov_b32_e32 v21, 0
	v_mov_b32_e32 v22, 0
	v_mov_b32_e32 v23, 0
	v_mov_b32_e32 v24, 0
	v_mov_b32_e32 v25, 0
	v_mov_b32_e32 v26, 0
	v_mov_b32_e32 v27, 0
	v_mov_b32_e32 v28, 0
	v_mov_b32_e32 v29, 0
	v_mov_b32_e32 v30, 0
	v_mov_b32_e32 v31, 0
.Lsgu_loop:
	s_cmp_lt_u32 s33, 2
	s_cbranch_scc1 .Lsgu_a_last
	s_ashr_i32 s42, s34, 6
	s_ashr_i32 s43, s42, 31
	s_and_b32 s22, s34, 48
	s_lshl_b64 s[42:43], s[42:43], 17
	s_lshl_b32 s22, s22, 1
	v_lshl_add_u64 v[210:211], v[32:33], 0, s[42:43]
	v_lshl_add_u64 v[210:211], v[210:211], 0, s[22:23]
	v_lshl_add_u64 v[210:211], v[210:211], 0, v[82:83]
	s_mov_b32 s42, 0x2000
	s_mov_b32 s43, 0
	global_load_dwordx4 v[38:41], v[34:35], off
	v_lshl_add_u64 v[212:213], v[210:211], 0, s[42:43]
	s_mov_b32 s42, 0x3000
	global_load_dwordx4 v[42:45], v[210:211], off
	global_load_dwordx4 v[46:49], v[210:211], off offset:2048
	v_lshl_add_u64 v[214:215], v[210:211], 0, s[42:43]
	global_load_dwordx4 v[50:53], v[212:213], off offset:-4096
	global_load_dwordx4 v[54:57], v[212:213], off offset:-2048
	global_load_dwordx4 v[194:197], v[212:213], off
	global_load_dwordx4 v[198:201], v[212:213], off offset:2048
	global_load_dwordx4 v[202:205], v[214:215], off
	global_load_dwordx4 v[206:209], v[214:215], off offset:2048
	s_add_i32 s34, s34, 32
	v_lshl_add_u64 v[34:35], v[34:35], 0, 64
	s_waitcnt vmcnt(9)
	v_mfma_f32_16x16x32_bf16 v[28:31], v[162:165], v[158:161], v[28:31]
	v_mfma_f32_16x16x32_bf16 v[24:27], v[166:169], v[158:161], v[24:27]
	v_mfma_f32_16x16x32_bf16 v[20:23], v[170:173], v[158:161], v[20:23]
	v_mfma_f32_16x16x32_bf16 v[16:19], v[174:177], v[158:161], v[16:19]
	v_mfma_f32_16x16x32_bf16 v[12:15], v[178:181], v[158:161], v[12:15]
	v_mfma_f32_16x16x32_bf16 v[8:11], v[182:185], v[158:161], v[8:11]
	v_mfma_f32_16x16x32_bf16 v[4:7], v[186:189], v[158:161], v[4:7]
	v_mfma_f32_16x16x32_bf16 v[0:3], v[190:193], v[158:161], v[0:3]
	s_sub_u32 s33, s33, 1
	s_cmp_lt_u32 s33, 2
	s_cbranch_scc1 .Lsgu_b_last
	s_ashr_i32 s42, s34, 6
	s_ashr_i32 s43, s42, 31
	s_and_b32 s22, s34, 48
	s_lshl_b64 s[42:43], s[42:43], 17
	s_lshl_b32 s22, s22, 1
	v_lshl_add_u64 v[210:211], v[32:33], 0, s[42:43]
	v_lshl_add_u64 v[210:211], v[210:211], 0, s[22:23]
	v_lshl_add_u64 v[210:211], v[210:211], 0, v[82:83]
	s_mov_b32 s42, 0x2000
	s_mov_b32 s43, 0
	global_load_dwordx4 v[158:161], v[34:35], off
	v_lshl_add_u64 v[212:213], v[210:211], 0, s[42:43]
	s_mov_b32 s42, 0x3000
	global_load_dwordx4 v[162:165], v[210:211], off
	global_load_dwordx4 v[166:169], v[210:211], off offset:2048
	v_lshl_add_u64 v[214:215], v[210:211], 0, s[42:43]
	global_load_dwordx4 v[170:173], v[212:213], off offset:-4096
	global_load_dwordx4 v[174:177], v[212:213], off offset:-2048
	global_load_dwordx4 v[178:181], v[212:213], off
	global_load_dwordx4 v[182:185], v[212:213], off offset:2048
	global_load_dwordx4 v[186:189], v[214:215], off
	global_load_dwordx4 v[190:193], v[214:215], off offset:2048
	s_add_i32 s34, s34, 32
	v_lshl_add_u64 v[34:35], v[34:35], 0, 64
	s_waitcnt vmcnt(9)
	v_mfma_f32_16x16x32_bf16 v[28:31], v[42:45], v[38:41], v[28:31]
	v_mfma_f32_16x16x32_bf16 v[24:27], v[46:49], v[38:41], v[24:27]
	v_mfma_f32_16x16x32_bf16 v[20:23], v[50:53], v[38:41], v[20:23]
	v_mfma_f32_16x16x32_bf16 v[16:19], v[54:57], v[38:41], v[16:19]
	v_mfma_f32_16x16x32_bf16 v[12:15], v[194:197], v[38:41], v[12:15]
	v_mfma_f32_16x16x32_bf16 v[8:11], v[198:201], v[38:41], v[8:11]
	v_mfma_f32_16x16x32_bf16 v[4:7], v[202:205], v[38:41], v[4:7]
	v_mfma_f32_16x16x32_bf16 v[0:3], v[206:209], v[38:41], v[0:3]
	s_sub_u32 s33, s33, 1
	s_branch .Lsgu_loop
; __device__ __forceinline__ unsigned pk2(float lo, float hi) { unsigned r; asm volatile("v_cvt_pk_bf16_f32 %0, %1, %2" : "=v"(r) : "v"(lo), "v"(hi)); return r; }
; __device__ __forceinline__ float bf_lo(unsigned w) { return __uint_as_float(w << 16); }
; __device__ __forceinline__ float bf_hi(unsigned w) { return __uint_as_float(w & 0xffff0000u); }
; __device__ __forceinline__ void p4_sgu_task(const bf16_t* Wsgu, const bf16_t* VT, const bf16_t* U, const float* sgu_b, bf16_t* MIX, int strip, int h, int lane) {
;     ...
;         for (int nf = 0; nf < 8; ++nf) { const bf16x8 b = *(const bf16x8*)(vb + (size_t)(16 * nf) * 64); acc[nf] = __builtin_amdgcn_mfma_f32_16x16x32_bf16(b, a, acc[nf], 0, 0, 0); }
;     }
;     const int tok = tok0 + fr; const float bias = sgu_b[h * 128 + t0 + fr];
; #pragma unroll
;     for (int nf = 0; nf < 8; ++nf) { const int col = h * 128 + 16 * nf + 4 * fq;
;         const u32x2 uw = *(const u32x2*)(U + (size_t)tok * AW + col);
;         const f32x4 s = acc[nf] + bias;
;         u32x2 w; w.x = pk2(bf_lo(uw.x) * s[0], bf_hi(uw.x) * s[1]); w.y = pk2(bf_lo(uw.y) * s[2], bf_hi(uw.y) * s[3]);
;         *(u32x2*)(MIX + (size_t)tok * D + col) = w; }
.Lsgu_a_last:
	s_waitcnt vmcnt(0)
	v_mfma_f32_16x16x32_bf16 v[28:31], v[162:165], v[158:161], v[28:31]
	v_mfma_f32_16x16x32_bf16 v[24:27], v[166:169], v[158:161], v[24:27]
	v_mfma_f32_16x16x32_bf16 v[20:23], v[170:173], v[158:161], v[20:23]
	v_mfma_f32_16x16x32_bf16 v[16:19], v[174:177], v[158:161], v[16:19]
	v_mfma_f32_16x16x32_bf16 v[12:15], v[178:181], v[158:161], v[12:15]
	v_mfma_f32_16x16x32_bf16 v[8:11], v[182:185], v[158:161], v[8:11]
	v_mfma_f32_16x16x32_bf16 v[4:7], v[186:189], v[158:161], v[4:7]
	v_mfma_f32_16x16x32_bf16 v[0:3], v[190:193], v[158:161], v[0:3]
	s_branch .Lsgu_epi
.Lsgu_b_last:
	s_waitcnt vmcnt(0)
	v_mfma_f32_16x16x32_bf16 v[28:31], v[42:45], v[38:41], v[28:31]
	v_mfma_f32_16x16x32_bf16 v[24:27], v[46:49], v[38:41], v[24:27]
	v_mfma_f32_16x16x32_bf16 v[20:23], v[50:53], v[38:41], v[20:23]
	v_mfma_f32_16x16x32_bf16 v[16:19], v[54:57], v[38:41], v[16:19]
	v_mfma_f32_16x16x32_bf16 v[12:15], v[194:197], v[38:41], v[12:15]
	v_mfma_f32_16x16x32_bf16 v[8:11], v[198:201], v[38:41], v[8:11]
	v_mfma_f32_16x16x32_bf16 v[4:7], v[202:205], v[38:41], v[4:7]
	v_mfma_f32_16x16x32_bf16 v[0:3], v[206:209], v[38:41], v[0:3]
.Lsgu_epi:
	s_nop 7
	s_nop 3
	v_add_f32_e32 v28, v28, v240
	v_add_f32_e32 v29, v29, v240
	v_add_f32_e32 v30, v30, v240
	v_add_f32_e32 v31, v31, v240
	v_lshlrev_b32_e32 v218, 16, v224
	v_and_b32_e32 v219, 0xffff0000, v224
	v_lshlrev_b32_e32 v220, 16, v225
	v_and_b32_e32 v221, 0xffff0000, v225
	v_mul_f32_e32 v28, v28, v218
	v_mul_f32_e32 v29, v29, v219
	v_mul_f32_e32 v30, v30, v220
	v_mul_f32_e32 v31, v31, v221
	v_cvt_pk_bf16_f32 v28, v28, v29
	v_cvt_pk_bf16_f32 v29, v30, v31
	global_store_dwordx2 v[244:245], v[28:29], off
	v_add_f32_e32 v24, v24, v240
	v_add_f32_e32 v25, v25, v240
	v_add_f32_e32 v26, v26, v240
	v_add_f32_e32 v27, v27, v240
	v_lshlrev_b32_e32 v218, 16, v226
	v_and_b32_e32 v219, 0xffff0000, v226
	v_lshlrev_b32_e32 v220, 16, v227
	v_and_b32_e32 v221, 0xffff0000, v227
	v_mul_f32_e32 v24, v24, v218
	v_mul_f32_e32 v25, v25, v219
	v_mul_f32_e32 v26, v26, v220
	v_mul_f32_e32 v27, v27, v221
	v_cvt_pk_bf16_f32 v24, v24, v25
	v_cvt_pk_bf16_f32 v25, v26, v27
	global_store_dwordx2 v[244:245], v[24:25], off offset:32
	v_add_f32_e32 v20, v20, v240
	v_add_f32_e32 v21, v21, v240
	v_add_f32_e32 v22, v22, v240
	v_add_f32_e32 v23, v23, v240
	v_lshlrev_b32_e32 v218, 16, v228
	v_and_b32_e32 v219, 0xffff0000, v228
	v_lshlrev_b32_e32 v220, 16, v229
	v_and_b32_e32 v221, 0xffff0000, v229
	v_mul_f32_e32 v20, v20, v218
	v_mul_f32_e32 v21, v21, v219
	v_mul_f32_e32 v22, v22, v220
	v_mul_f32_e32 v23, v23, v221
	v_cvt_pk_bf16_f32 v20, v20, v21
	v_cvt_pk_bf16_f32 v21, v22, v23
	global_store_dwordx2 v[244:245], v[20:21], off offset:64
	v_add_f32_e32 v16, v16, v240
	v_add_f32_e32 v17, v17, v240
	v_add_f32_e32 v18, v18, v240
	v_add_f32_e32 v19, v19, v240
	v_lshlrev_b32_e32 v218, 16, v230
	v_and_b32_e32 v219, 0xffff0000, v230
	v_lshlrev_b32_e32 v220, 16, v231
	v_and_b32_e32 v221, 0xffff0000, v231
	v_mul_f32_e32 v16, v16, v218
	v_mul_f32_e32 v17, v17, v219
	v_mul_f32_e32 v18, v18, v220
	v_mul_f32_e32 v19, v19, v221
	v_cvt_pk_bf16_f32 v16, v16, v17
	v_cvt_pk_bf16_f32 v17, v18, v19
	global_store_dwordx2 v[244:245], v[16:17], off offset:96
	v_add_f32_e32 v12, v12, v240
	v_add_f32_e32 v13, v13, v240
	v_add_f32_e32 v14, v14, v240
	v_add_f32_e32 v15, v15, v240
	v_lshlrev_b32_e32 v218, 16, v232
	v_and_b32_e32 v219, 0xffff0000, v232
	v_lshlrev_b32_e32 v220, 16, v233
	v_and_b32_e32 v221, 0xffff0000, v233
	v_mul_f32_e32 v12, v12, v218
	v_mul_f32_e32 v13, v13, v219
	v_mul_f32_e32 v14, v14, v220
	v_mul_f32_e32 v15, v15, v221
	v_cvt_pk_bf16_f32 v12, v12, v13
	v_cvt_pk_bf16_f32 v13, v14, v15
	global_store_dwordx2 v[244:245], v[12:13], off offset:128
	v_add_f32_e32 v8, v8, v240
	v_add_f32_e32 v9, v9, v240
	v_add_f32_e32 v10, v10, v240
	v_add_f32_e32 v11, v11, v240
	v_lshlrev_b32_e32 v218, 16, v234
	v_and_b32_e32 v219, 0xffff0000, v234
	v_lshlrev_b32_e32 v220, 16, v235
	v_and_b32_e32 v221, 0xffff0000, v235
	v_mul_f32_e32 v8, v8, v218
	v_mul_f32_e32 v9, v9, v219
	v_mul_f32_e32 v10, v10, v220
	v_mul_f32_e32 v11, v11, v221
	v_cvt_pk_bf16_f32 v8, v8, v9
	v_cvt_pk_bf16_f32 v9, v10, v11
	global_store_dwordx2 v[244:245], v[8:9], off offset:160
	v_add_f32_e32 v4, v4, v240
	v_add_f32_e32 v5, v5, v240
	v_add_f32_e32 v6, v6, v240
	v_add_f32_e32 v7, v7, v240
	v_lshlrev_b32_e32 v218, 16, v236
	v_and_b32_e32 v219, 0xffff0000, v236
	v_lshlrev_b32_e32 v220, 16, v237
	v_and_b32_e32 v221, 0xffff0000, v237
	v_mul_f32_e32 v4, v4, v218
	v_mul_f32_e32 v5, v5, v219
	v_mul_f32_e32 v6, v6, v220
	v_mul_f32_e32 v7, v7, v221
	v_cvt_pk_bf16_f32 v4, v4, v5
	v_cvt_pk_bf16_f32 v5, v6, v7
	global_store_dwordx2 v[244:245], v[4:5], off offset:192
	v_add_f32_e32 v0, v0, v240
	v_add_f32_e32 v1, v1, v240
	v_add_f32_e32 v2, v2, v240
	v_add_f32_e32 v3, v3, v240
	v_lshlrev_b32_e32 v218, 16, v238
	v_and_b32_e32 v219, 0xffff0000, v238
	v_lshlrev_b32_e32 v220, 16, v239
	v_and_b32_e32 v221, 0xffff0000, v239
	v_mul_f32_e32 v0, v0, v218
	v_mul_f32_e32 v1, v1, v219
	v_mul_f32_e32 v2, v2, v220
	v_mul_f32_e32 v3, v3, v221
	v_cvt_pk_bf16_f32 v0, v0, v1
	v_cvt_pk_bf16_f32 v1, v2, v3
	global_store_dwordx2 v[244:245], v[0:1], off offset:224
	s_mov_b64 s[8:9], 0
